# v76 plus G2 LRU-scan-first reordering and gla_g3 load hoists (q/k/v/state loads and epilogue gate loads issued together)
# baseline (speedup 1.0000x reference)
.LBB0_117:
	s_andn2_b64 vcc, exec, s[0:1]
	s_cbranch_vccnz .LBB0_129
	s_waitcnt lgkmcnt(0)
	s_mov_b32 s100, 0
